# RWKV recurrence chunk loop rewritten by hand: LDS reads of a step issued as one burst with a single counted wait, row sums of y reduced with bank-masked DPP, chain ops back to back
# speedup vs baseline: 1.0184x; 1.0184x over previous
.LBB0_2881:
	s_and_b32 s2, s50, 1
	s_mul_i32 s18, s2, 0xa800
	s_add_i32 s18, s18, 0
	v_add_u32_e32 v50, s18, v0
	v_add3_u32 v51, s18, v47, v48
	v_lshl_add_u32 v52, s2, 11, v49
	s_add_i32 s50, s50, 1
	s_waitcnt vmcnt(0)
	ds_read_b128 v[6:9], v50 offset:512
	ds_read_b128 v[10:13], v50 offset:256
	ds_read_b128 v[14:17], v50 offset:0
	ds_read_b128 v[18:21], v50 offset:768
	ds_read_b128 v[22:25], v50 offset:1024
	ds_read_b128 v[54:57], v51 offset:1280
	ds_read_b128 v[26:29], v50 offset:1856
	s_waitcnt lgkmcnt(6)
	v_pk_mul_f32 v[6:7], v[2:3], v[6:7]
	v_pk_fma_f32 v[6:7], v[4:5], v[8:9], v[6:7]
	v_add_f32_e32 v72, v6, v7
	ds_read_b128 v[6:9], v50 offset:3200
	ds_read_b128 v[42:45], v50 offset:2368
	ds_read_b128 v[38:41], v50 offset:2112
	ds_read_b128 v[34:37], v50 offset:1344
	ds_read_b128 v[30:33], v50 offset:1600
	ds_read_b128 v[58:61], v51 offset:6656
	s_waitcnt lgkmcnt(6)
	v_add_f32_dpp v72, v72, v72 row_ror:8 row_mask:0xf bank_mask:0xf bound_ctrl:1
	v_pk_mul_f32 v[68:69], v[18:19], v[54:55] op_sel_hi:[1,0]
	v_pk_mul_f32 v[70:71], v[20:21], v[54:55] op_sel_hi:[1,0]
	v_add_f32_dpp v72, v72, v72 row_ror:4 row_mask:0xf bank_mask:0xf bound_ctrl:1
	v_pk_fma_f32 v[68:69], v[2:3], v[14:15], v[68:69]
	v_pk_fma_f32 v[70:71], v[4:5], v[16:17], v[70:71]
	v_add_f32_dpp v72, v72, v72 row_ror:2 row_mask:0xf bank_mask:0xf bound_ctrl:1
	s_nop 0
	s_nop 0
	v_add_f32_dpp v72, v72, v72 row_ror:1 row_mask:0xf bank_mask:0xf bound_ctrl:1
	v_pk_fma_f32 v[2:3], v[10:11], v[72:73], v[68:69] op_sel_hi:[1,0,1]
	v_pk_fma_f32 v[4:5], v[12:13], v[72:73], v[70:71] op_sel_hi:[1,0,1]
	v_pk_mul_f32 v[26:27], v[2:3], v[26:27]
	v_pk_fma_f32 v[26:27], v[4:5], v[28:29], v[26:27]
	v_add_f32_e32 v72, v26, v27
	ds_read_b128 v[26:29], v50 offset:4544
	ds_read_b128 v[190:193], v50 offset:3712
	ds_read_b128 v[18:21], v50 offset:3456
	ds_read_b128 v[14:17], v50 offset:2688
	ds_read_b128 v[10:13], v50 offset:2944
	s_waitcnt lgkmcnt(5)
	v_add_f32_dpp v72, v72, v72 row_ror:8 row_mask:0xf bank_mask:0xf bound_ctrl:1
	v_pk_mul_f32 v[68:69], v[38:39], v[54:55] op_sel:[0,1]
	v_pk_mul_f32 v[70:71], v[40:41], v[54:55] op_sel:[0,1]
	v_add_f32_dpp v72, v72, v72 row_ror:4 row_mask:0xf bank_mask:0xf bound_ctrl:1
	v_pk_fma_f32 v[68:69], v[2:3], v[34:35], v[68:69]
	v_pk_fma_f32 v[70:71], v[4:5], v[36:37], v[70:71]
	v_add_f32_dpp v72, v72, v72 row_ror:2 row_mask:0xf bank_mask:0xf bound_ctrl:1
	v_pk_mul_f32 v[184:185], v[24:25], v[4:5]
	v_pk_fma_f32 v[184:185], v[22:23], v[2:3], v[184:185]
	v_add_f32_dpp v72, v72, v72 row_ror:1 row_mask:0xf bank_mask:0xf bound_ctrl:1
	v_pk_fma_f32 v[2:3], v[30:31], v[72:73], v[68:69] op_sel_hi:[1,0,1]
	v_pk_fma_f32 v[4:5], v[32:33], v[72:73], v[70:71] op_sel_hi:[1,0,1]
	v_add_f32_e32 v62, v184, v185
	v_pk_mul_f32 v[6:7], v[2:3], v[6:7]
	v_pk_fma_f32 v[6:7], v[4:5], v[8:9], v[6:7]
	v_add_f32_e32 v72, v6, v7
	ds_read_b128 v[6:9], v50 offset:5888
	ds_read_b128 v[22:25], v50 offset:5056
	ds_read_b128 v[38:41], v50 offset:4800
	ds_read_b128 v[34:37], v50 offset:4032
	ds_read_b128 v[30:33], v50 offset:4288
	s_waitcnt lgkmcnt(5)
	v_add_f32_dpp v72, v72, v72 row_ror:8 row_mask:0xf bank_mask:0xf bound_ctrl:1
	v_pk_mul_f32 v[68:69], v[18:19], v[56:57] op_sel_hi:[1,0]
	v_pk_mul_f32 v[70:71], v[20:21], v[56:57] op_sel_hi:[1,0]
	v_add_f32_dpp v72, v72, v72 row_ror:4 row_mask:0xf bank_mask:0xf bound_ctrl:1
	v_pk_fma_f32 v[68:69], v[2:3], v[14:15], v[68:69]
	v_pk_fma_f32 v[70:71], v[4:5], v[16:17], v[70:71]
	v_add_f32_dpp v72, v72, v72 row_ror:2 row_mask:0xf bank_mask:0xf bound_ctrl:1
	v_pk_mul_f32 v[184:185], v[44:45], v[4:5]
	v_pk_fma_f32 v[184:185], v[42:43], v[2:3], v[184:185]
	v_add_f32_dpp v72, v72, v72 row_ror:1 row_mask:0xf bank_mask:0xf bound_ctrl:1
	v_pk_fma_f32 v[2:3], v[10:11], v[72:73], v[68:69] op_sel_hi:[1,0,1]
	v_pk_fma_f32 v[4:5], v[12:13], v[72:73], v[70:71] op_sel_hi:[1,0,1]
	v_add_f32_e32 v63, v184, v185
	v_pk_mul_f32 v[26:27], v[2:3], v[26:27]
	v_pk_fma_f32 v[26:27], v[4:5], v[28:29], v[26:27]
	v_add_f32_e32 v72, v26, v27
	ds_read_b128 v[26:29], v50 offset:7232
	ds_read_b128 v[42:45], v50 offset:6400
	ds_read_b128 v[18:21], v50 offset:6144
	ds_read_b128 v[14:17], v50 offset:5376
	ds_read_b128 v[10:13], v50 offset:5632
	s_waitcnt lgkmcnt(5)
	v_add_f32_dpp v72, v72, v72 row_ror:8 row_mask:0xf bank_mask:0xf bound_ctrl:1
	v_pk_mul_f32 v[68:69], v[38:39], v[56:57] op_sel:[0,1]
	v_pk_mul_f32 v[70:71], v[40:41], v[56:57] op_sel:[0,1]
	v_add_f32_dpp v72, v72, v72 row_ror:4 row_mask:0xf bank_mask:0xf bound_ctrl:1
	v_pk_fma_f32 v[68:69], v[2:3], v[34:35], v[68:69]
	v_pk_fma_f32 v[70:71], v[4:5], v[36:37], v[70:71]
	v_add_f32_dpp v72, v72, v72 row_ror:2 row_mask:0xf bank_mask:0xf bound_ctrl:1
	v_pk_mul_f32 v[184:185], v[192:193], v[4:5]
	v_pk_fma_f32 v[184:185], v[190:191], v[2:3], v[184:185]
	v_add_f32_dpp v72, v72, v72 row_ror:1 row_mask:0xf bank_mask:0xf bound_ctrl:1
	v_pk_fma_f32 v[2:3], v[30:31], v[72:73], v[68:69] op_sel_hi:[1,0,1]
	v_pk_fma_f32 v[4:5], v[32:33], v[72:73], v[70:71] op_sel_hi:[1,0,1]
	v_add_f32_e32 v64, v184, v185
	v_pk_mul_f32 v[6:7], v[2:3], v[6:7]
	v_pk_fma_f32 v[6:7], v[4:5], v[8:9], v[6:7]
	v_add_f32_e32 v72, v6, v7
	ds_read_b128 v[6:9], v50 offset:8576
	ds_read_b128 v[190:193], v50 offset:7744
	ds_read_b128 v[38:41], v50 offset:7488
	ds_read_b128 v[34:37], v50 offset:6720
	ds_read_b128 v[30:33], v50 offset:6976
	ds_read_b128 v[54:57], v51 offset:12032
	s_waitcnt lgkmcnt(6)
	v_add_f32_dpp v62, v62, v62 row_ror:8 row_mask:0xf bank_mask:0x3 bound_ctrl:1
	v_add_f32_dpp v72, v72, v72 row_ror:8 row_mask:0xf bank_mask:0xf bound_ctrl:1
	v_pk_mul_f32 v[68:69], v[18:19], v[58:59] op_sel_hi:[1,0]
	v_pk_mul_f32 v[70:71], v[20:21], v[58:59] op_sel_hi:[1,0]
	v_add_f32_dpp v72, v72, v72 row_ror:4 row_mask:0xf bank_mask:0xf bound_ctrl:1
	v_pk_fma_f32 v[68:69], v[2:3], v[14:15], v[68:69]
	v_pk_fma_f32 v[70:71], v[4:5], v[16:17], v[70:71]
	v_add_f32_dpp v72, v72, v72 row_ror:2 row_mask:0xf bank_mask:0xf bound_ctrl:1
	v_pk_mul_f32 v[184:185], v[24:25], v[4:5]
	v_pk_fma_f32 v[184:185], v[22:23], v[2:3], v[184:185]
	v_add_f32_dpp v72, v72, v72 row_ror:1 row_mask:0xf bank_mask:0xf bound_ctrl:1
	v_pk_fma_f32 v[2:3], v[10:11], v[72:73], v[68:69] op_sel_hi:[1,0,1]
	v_pk_fma_f32 v[4:5], v[12:13], v[72:73], v[70:71] op_sel_hi:[1,0,1]
	v_add_f32_e32 v65, v184, v185
	v_add_f32_dpp v63, v63, v63 row_ror:8 row_mask:0xf bank_mask:0x3 bound_ctrl:1
	v_pk_mul_f32 v[26:27], v[2:3], v[26:27]
	v_pk_fma_f32 v[26:27], v[4:5], v[28:29], v[26:27]
	v_add_f32_e32 v72, v26, v27
	ds_read_b128 v[26:29], v50 offset:9920
	ds_read_b128 v[22:25], v50 offset:9088
	ds_read_b128 v[18:21], v50 offset:8832
	ds_read_b128 v[14:17], v50 offset:8064
	ds_read_b128 v[10:13], v50 offset:8320
	s_waitcnt lgkmcnt(5)
	v_add_f32_dpp v62, v64, v64 row_ror:8 row_mask:0xf bank_mask:0xc bound_ctrl:1
	v_add_f32_dpp v72, v72, v72 row_ror:8 row_mask:0xf bank_mask:0xf bound_ctrl:1
	v_pk_mul_f32 v[68:69], v[38:39], v[58:59] op_sel:[0,1]
	v_pk_mul_f32 v[70:71], v[40:41], v[58:59] op_sel:[0,1]
	v_add_f32_dpp v72, v72, v72 row_ror:4 row_mask:0xf bank_mask:0xf bound_ctrl:1
	v_pk_fma_f32 v[68:69], v[2:3], v[34:35], v[68:69]
	v_pk_fma_f32 v[70:71], v[4:5], v[36:37], v[70:71]
	v_add_f32_dpp v72, v72, v72 row_ror:2 row_mask:0xf bank_mask:0xf bound_ctrl:1
	v_pk_mul_f32 v[184:185], v[44:45], v[4:5]
	v_pk_fma_f32 v[184:185], v[42:43], v[2:3], v[184:185]
	v_add_f32_dpp v72, v72, v72 row_ror:1 row_mask:0xf bank_mask:0xf bound_ctrl:1
	v_pk_fma_f32 v[2:3], v[30:31], v[72:73], v[68:69] op_sel_hi:[1,0,1]
	v_pk_fma_f32 v[4:5], v[32:33], v[72:73], v[70:71] op_sel_hi:[1,0,1]
	v_add_f32_e32 v186, v184, v185
	v_add_f32_dpp v63, v65, v65 row_ror:8 row_mask:0xf bank_mask:0xc bound_ctrl:1
	v_pk_mul_f32 v[6:7], v[2:3], v[6:7]
	v_pk_fma_f32 v[6:7], v[4:5], v[8:9], v[6:7]
	v_add_f32_e32 v72, v6, v7
	ds_read_b128 v[6:9], v50 offset:11264
	ds_read_b128 v[42:45], v50 offset:10432
	ds_read_b128 v[38:41], v50 offset:10176
	ds_read_b128 v[34:37], v50 offset:9408
	ds_read_b128 v[30:33], v50 offset:9664
	s_waitcnt lgkmcnt(5)
	v_add_f32_dpp v62, v62, v62 row_half_mirror row_mask:0xf bank_mask:0x5 bound_ctrl:1
	v_add_f32_dpp v72, v72, v72 row_ror:8 row_mask:0xf bank_mask:0xf bound_ctrl:1
	v_pk_mul_f32 v[68:69], v[18:19], v[60:61] op_sel_hi:[1,0]
	v_pk_mul_f32 v[70:71], v[20:21], v[60:61] op_sel_hi:[1,0]
	v_add_f32_dpp v72, v72, v72 row_ror:4 row_mask:0xf bank_mask:0xf bound_ctrl:1
	v_pk_fma_f32 v[68:69], v[2:3], v[14:15], v[68:69]
	v_pk_fma_f32 v[70:71], v[4:5], v[16:17], v[70:71]
	v_add_f32_dpp v72, v72, v72 row_ror:2 row_mask:0xf bank_mask:0xf bound_ctrl:1
	v_pk_mul_f32 v[184:185], v[192:193], v[4:5]
	v_pk_fma_f32 v[184:185], v[190:191], v[2:3], v[184:185]
	v_add_f32_dpp v72, v72, v72 row_ror:1 row_mask:0xf bank_mask:0xf bound_ctrl:1
	v_pk_fma_f32 v[2:3], v[10:11], v[72:73], v[68:69] op_sel_hi:[1,0,1]
	v_pk_fma_f32 v[4:5], v[12:13], v[72:73], v[70:71] op_sel_hi:[1,0,1]
	v_add_f32_e32 v187, v184, v185
	v_add_f32_dpp v62, v63, v63 row_half_mirror row_mask:0xf bank_mask:0xa bound_ctrl:1
	v_pk_mul_f32 v[26:27], v[2:3], v[26:27]
	v_pk_fma_f32 v[26:27], v[4:5], v[28:29], v[26:27]
	v_add_f32_e32 v72, v26, v27
	ds_read_b128 v[26:29], v50 offset:12608
	ds_read_b128 v[190:193], v50 offset:11776
	ds_read_b128 v[18:21], v50 offset:11520
	ds_read_b128 v[14:17], v50 offset:10752
	ds_read_b128 v[10:13], v50 offset:11008
	s_waitcnt lgkmcnt(5)
	v_add_f32_dpp v62, v62, v62 quad_perm:[1,0,3,2] row_mask:0xf bank_mask:0xf bound_ctrl:1
	v_add_f32_dpp v72, v72, v72 row_ror:8 row_mask:0xf bank_mask:0xf bound_ctrl:1
	v_pk_mul_f32 v[68:69], v[38:39], v[60:61] op_sel:[0,1]
	v_pk_mul_f32 v[70:71], v[40:41], v[60:61] op_sel:[0,1]
	v_add_f32_dpp v72, v72, v72 row_ror:4 row_mask:0xf bank_mask:0xf bound_ctrl:1
	v_pk_fma_f32 v[68:69], v[2:3], v[34:35], v[68:69]
	v_pk_fma_f32 v[70:71], v[4:5], v[36:37], v[70:71]
	v_add_f32_dpp v72, v72, v72 row_ror:2 row_mask:0xf bank_mask:0xf bound_ctrl:1
	v_pk_mul_f32 v[184:185], v[24:25], v[4:5]
	v_pk_fma_f32 v[184:185], v[22:23], v[2:3], v[184:185]
	v_add_f32_dpp v72, v72, v72 row_ror:1 row_mask:0xf bank_mask:0xf bound_ctrl:1
	v_pk_fma_f32 v[2:3], v[30:31], v[72:73], v[68:69] op_sel_hi:[1,0,1]
	v_pk_fma_f32 v[4:5], v[32:33], v[72:73], v[70:71] op_sel_hi:[1,0,1]
	v_add_f32_e32 v188, v184, v185
	v_add_f32_dpp v62, v62, v62 quad_perm:[2,3,0,1] row_mask:0xf bank_mask:0xf bound_ctrl:1
	v_pk_mul_f32 v[6:7], v[2:3], v[6:7]
	v_pk_fma_f32 v[6:7], v[4:5], v[8:9], v[6:7]
	v_add_f32_e32 v72, v6, v7
	ds_read_b128 v[6:9], v50 offset:13952
	ds_read_b128 v[22:25], v50 offset:13120
	ds_read_b128 v[38:41], v50 offset:12864
	ds_read_b128 v[34:37], v50 offset:12096
	ds_read_b128 v[30:33], v50 offset:12352
	ds_read_b128 v[58:61], v51 offset:17408
	s_waitcnt lgkmcnt(6)
	v_cndmask_b32_e64 v66, 0, v62, s[6:7]
	v_add_f32_dpp v72, v72, v72 row_ror:8 row_mask:0xf bank_mask:0xf bound_ctrl:1
	v_pk_mul_f32 v[68:69], v[18:19], v[54:55] op_sel_hi:[1,0]
	v_pk_mul_f32 v[70:71], v[20:21], v[54:55] op_sel_hi:[1,0]
	v_add_f32_dpp v72, v72, v72 row_ror:4 row_mask:0xf bank_mask:0xf bound_ctrl:1
	v_pk_fma_f32 v[68:69], v[2:3], v[14:15], v[68:69]
	v_pk_fma_f32 v[70:71], v[4:5], v[16:17], v[70:71]
	v_add_f32_dpp v72, v72, v72 row_ror:2 row_mask:0xf bank_mask:0xf bound_ctrl:1
	v_pk_mul_f32 v[184:185], v[44:45], v[4:5]
	v_pk_fma_f32 v[184:185], v[42:43], v[2:3], v[184:185]
	v_add_f32_dpp v72, v72, v72 row_ror:1 row_mask:0xf bank_mask:0xf bound_ctrl:1
	v_pk_fma_f32 v[2:3], v[10:11], v[72:73], v[68:69] op_sel_hi:[1,0,1]
	v_pk_fma_f32 v[4:5], v[12:13], v[72:73], v[70:71] op_sel_hi:[1,0,1]
	v_add_f32_e32 v189, v184, v185
	v_add_f32_dpp v186, v186, v186 row_ror:8 row_mask:0xf bank_mask:0x3 bound_ctrl:1
	v_pk_mul_f32 v[26:27], v[2:3], v[26:27]
	v_pk_fma_f32 v[26:27], v[4:5], v[28:29], v[26:27]
	v_add_f32_e32 v72, v26, v27
	ds_read_b128 v[26:29], v50 offset:15296
	ds_read_b128 v[42:45], v50 offset:14464
	ds_read_b128 v[18:21], v50 offset:14208
	ds_read_b128 v[14:17], v50 offset:13440
	ds_read_b128 v[10:13], v50 offset:13696
	s_waitcnt lgkmcnt(5)
	v_add_f32_dpp v187, v187, v187 row_ror:8 row_mask:0xf bank_mask:0x3 bound_ctrl:1
	v_add_f32_dpp v72, v72, v72 row_ror:8 row_mask:0xf bank_mask:0xf bound_ctrl:1
	v_pk_mul_f32 v[68:69], v[38:39], v[54:55] op_sel:[0,1]
	v_pk_mul_f32 v[70:71], v[40:41], v[54:55] op_sel:[0,1]
	v_add_f32_dpp v72, v72, v72 row_ror:4 row_mask:0xf bank_mask:0xf bound_ctrl:1
	v_pk_fma_f32 v[68:69], v[2:3], v[34:35], v[68:69]
	v_pk_fma_f32 v[70:71], v[4:5], v[36:37], v[70:71]
	v_add_f32_dpp v72, v72, v72 row_ror:2 row_mask:0xf bank_mask:0xf bound_ctrl:1
	v_pk_mul_f32 v[184:185], v[192:193], v[4:5]
	v_pk_fma_f32 v[184:185], v[190:191], v[2:3], v[184:185]
	v_add_f32_dpp v72, v72, v72 row_ror:1 row_mask:0xf bank_mask:0xf bound_ctrl:1
	v_pk_fma_f32 v[2:3], v[30:31], v[72:73], v[68:69] op_sel_hi:[1,0,1]
	v_pk_fma_f32 v[4:5], v[32:33], v[72:73], v[70:71] op_sel_hi:[1,0,1]
	v_add_f32_e32 v62, v184, v185
	v_add_f32_dpp v186, v188, v188 row_ror:8 row_mask:0xf bank_mask:0xc bound_ctrl:1
	v_pk_mul_f32 v[6:7], v[2:3], v[6:7]
	v_pk_fma_f32 v[6:7], v[4:5], v[8:9], v[6:7]
	v_add_f32_e32 v72, v6, v7
	ds_read_b128 v[6:9], v50 offset:16640
	ds_read_b128 v[190:193], v50 offset:15808
	ds_read_b128 v[38:41], v50 offset:15552
	ds_read_b128 v[34:37], v50 offset:14784
	ds_read_b128 v[30:33], v50 offset:15040
	s_waitcnt lgkmcnt(5)
	v_add_f32_dpp v187, v189, v189 row_ror:8 row_mask:0xf bank_mask:0xc bound_ctrl:1
	v_add_f32_dpp v72, v72, v72 row_ror:8 row_mask:0xf bank_mask:0xf bound_ctrl:1
	v_pk_mul_f32 v[68:69], v[18:19], v[56:57] op_sel_hi:[1,0]
	v_pk_mul_f32 v[70:71], v[20:21], v[56:57] op_sel_hi:[1,0]
	v_add_f32_dpp v72, v72, v72 row_ror:4 row_mask:0xf bank_mask:0xf bound_ctrl:1
	v_pk_fma_f32 v[68:69], v[2:3], v[14:15], v[68:69]
	v_pk_fma_f32 v[70:71], v[4:5], v[16:17], v[70:71]
	v_add_f32_dpp v72, v72, v72 row_ror:2 row_mask:0xf bank_mask:0xf bound_ctrl:1
	v_pk_mul_f32 v[184:185], v[24:25], v[4:5]
	v_pk_fma_f32 v[184:185], v[22:23], v[2:3], v[184:185]
	v_add_f32_dpp v72, v72, v72 row_ror:1 row_mask:0xf bank_mask:0xf bound_ctrl:1
	v_pk_fma_f32 v[2:3], v[10:11], v[72:73], v[68:69] op_sel_hi:[1,0,1]
	v_pk_fma_f32 v[4:5], v[12:13], v[72:73], v[70:71] op_sel_hi:[1,0,1]
	v_add_f32_e32 v63, v184, v185
	v_add_f32_dpp v186, v186, v186 row_half_mirror row_mask:0xf bank_mask:0x5 bound_ctrl:1
	v_pk_mul_f32 v[26:27], v[2:3], v[26:27]
	v_pk_fma_f32 v[26:27], v[4:5], v[28:29], v[26:27]
	v_add_f32_e32 v72, v26, v27
	ds_read_b128 v[26:29], v50 offset:17984
	ds_read_b128 v[22:25], v50 offset:17152
	ds_read_b128 v[18:21], v50 offset:16896
	ds_read_b128 v[14:17], v50 offset:16128
	ds_read_b128 v[10:13], v50 offset:16384
	s_waitcnt lgkmcnt(5)
	v_add_f32_dpp v186, v187, v187 row_half_mirror row_mask:0xf bank_mask:0xa bound_ctrl:1
	v_add_f32_dpp v72, v72, v72 row_ror:8 row_mask:0xf bank_mask:0xf bound_ctrl:1
	v_pk_mul_f32 v[68:69], v[38:39], v[56:57] op_sel:[0,1]
	v_pk_mul_f32 v[70:71], v[40:41], v[56:57] op_sel:[0,1]
	v_add_f32_dpp v72, v72, v72 row_ror:4 row_mask:0xf bank_mask:0xf bound_ctrl:1
	v_pk_fma_f32 v[68:69], v[2:3], v[34:35], v[68:69]
	v_pk_fma_f32 v[70:71], v[4:5], v[36:37], v[70:71]
	v_add_f32_dpp v72, v72, v72 row_ror:2 row_mask:0xf bank_mask:0xf bound_ctrl:1
	v_pk_mul_f32 v[184:185], v[44:45], v[4:5]
	v_pk_fma_f32 v[184:185], v[42:43], v[2:3], v[184:185]
	v_add_f32_dpp v72, v72, v72 row_ror:1 row_mask:0xf bank_mask:0xf bound_ctrl:1
	v_pk_fma_f32 v[2:3], v[30:31], v[72:73], v[68:69] op_sel_hi:[1,0,1]
	v_pk_fma_f32 v[4:5], v[32:33], v[72:73], v[70:71] op_sel_hi:[1,0,1]
	v_add_f32_e32 v64, v184, v185
	v_add_f32_dpp v186, v186, v186 quad_perm:[1,0,3,2] row_mask:0xf bank_mask:0xf bound_ctrl:1
	v_pk_mul_f32 v[6:7], v[2:3], v[6:7]
	v_pk_fma_f32 v[6:7], v[4:5], v[8:9], v[6:7]
	v_add_f32_e32 v72, v6, v7
	ds_read_b128 v[6:9], v50 offset:19328
	ds_read_b128 v[42:45], v50 offset:18496
	ds_read_b128 v[38:41], v50 offset:18240
	ds_read_b128 v[34:37], v50 offset:17472
	ds_read_b128 v[30:33], v50 offset:17728
	ds_read_b128 v[54:57], v51 offset:22784
	s_waitcnt lgkmcnt(6)
	v_add_f32_dpp v186, v186, v186 quad_perm:[2,3,0,1] row_mask:0xf bank_mask:0xf bound_ctrl:1
	v_add_f32_dpp v72, v72, v72 row_ror:8 row_mask:0xf bank_mask:0xf bound_ctrl:1
	v_pk_mul_f32 v[68:69], v[18:19], v[58:59] op_sel_hi:[1,0]
	v_pk_mul_f32 v[70:71], v[20:21], v[58:59] op_sel_hi:[1,0]
	v_add_f32_dpp v72, v72, v72 row_ror:4 row_mask:0xf bank_mask:0xf bound_ctrl:1
	v_pk_fma_f32 v[68:69], v[2:3], v[14:15], v[68:69]
	v_pk_fma_f32 v[70:71], v[4:5], v[16:17], v[70:71]
	v_add_f32_dpp v72, v72, v72 row_ror:2 row_mask:0xf bank_mask:0xf bound_ctrl:1
	v_pk_mul_f32 v[184:185], v[192:193], v[4:5]
	v_pk_fma_f32 v[184:185], v[190:191], v[2:3], v[184:185]
	v_add_f32_dpp v72, v72, v72 row_ror:1 row_mask:0xf bank_mask:0xf bound_ctrl:1
	v_pk_fma_f32 v[2:3], v[10:11], v[72:73], v[68:69] op_sel_hi:[1,0,1]
	v_pk_fma_f32 v[4:5], v[12:13], v[72:73], v[70:71] op_sel_hi:[1,0,1]
	v_add_f32_e32 v65, v184, v185
	v_cndmask_b32_e64 v66, v66, v186, s[8:9]
	v_pk_mul_f32 v[26:27], v[2:3], v[26:27]
	v_pk_fma_f32 v[26:27], v[4:5], v[28:29], v[26:27]
	v_add_f32_e32 v72, v26, v27
	ds_read_b128 v[26:29], v50 offset:20672
	ds_read_b128 v[190:193], v50 offset:19840
	ds_read_b128 v[18:21], v50 offset:19584
	ds_read_b128 v[14:17], v50 offset:18816
	ds_read_b128 v[10:13], v50 offset:19072
	s_waitcnt lgkmcnt(5)
	v_add_f32_dpp v62, v62, v62 row_ror:8 row_mask:0xf bank_mask:0x3 bound_ctrl:1
	v_add_f32_dpp v72, v72, v72 row_ror:8 row_mask:0xf bank_mask:0xf bound_ctrl:1
	v_pk_mul_f32 v[68:69], v[38:39], v[58:59] op_sel:[0,1]
	v_pk_mul_f32 v[70:71], v[40:41], v[58:59] op_sel:[0,1]
	v_add_f32_dpp v72, v72, v72 row_ror:4 row_mask:0xf bank_mask:0xf bound_ctrl:1
	v_pk_fma_f32 v[68:69], v[2:3], v[34:35], v[68:69]
	v_pk_fma_f32 v[70:71], v[4:5], v[36:37], v[70:71]
	v_add_f32_dpp v72, v72, v72 row_ror:2 row_mask:0xf bank_mask:0xf bound_ctrl:1
	v_pk_mul_f32 v[184:185], v[24:25], v[4:5]
	v_pk_fma_f32 v[184:185], v[22:23], v[2:3], v[184:185]
	v_add_f32_dpp v72, v72, v72 row_ror:1 row_mask:0xf bank_mask:0xf bound_ctrl:1
	v_pk_fma_f32 v[2:3], v[30:31], v[72:73], v[68:69] op_sel_hi:[1,0,1]
	v_pk_fma_f32 v[4:5], v[32:33], v[72:73], v[70:71] op_sel_hi:[1,0,1]
	v_add_f32_e32 v186, v184, v185
	v_add_f32_dpp v63, v63, v63 row_ror:8 row_mask:0xf bank_mask:0x3 bound_ctrl:1
	v_pk_mul_f32 v[6:7], v[2:3], v[6:7]
	v_pk_fma_f32 v[6:7], v[4:5], v[8:9], v[6:7]
	v_add_f32_e32 v72, v6, v7
	ds_read_b128 v[6:9], v50 offset:22016
	ds_read_b128 v[22:25], v50 offset:21184
	ds_read_b128 v[38:41], v50 offset:20928
	ds_read_b128 v[34:37], v50 offset:20160
	ds_read_b128 v[30:33], v50 offset:20416
	s_waitcnt lgkmcnt(5)
	v_add_f32_dpp v62, v64, v64 row_ror:8 row_mask:0xf bank_mask:0xc bound_ctrl:1
	v_add_f32_dpp v72, v72, v72 row_ror:8 row_mask:0xf bank_mask:0xf bound_ctrl:1
	v_pk_mul_f32 v[68:69], v[18:19], v[60:61] op_sel_hi:[1,0]
	v_pk_mul_f32 v[70:71], v[20:21], v[60:61] op_sel_hi:[1,0]
	v_add_f32_dpp v72, v72, v72 row_ror:4 row_mask:0xf bank_mask:0xf bound_ctrl:1
	v_pk_fma_f32 v[68:69], v[2:3], v[14:15], v[68:69]
	v_pk_fma_f32 v[70:71], v[4:5], v[16:17], v[70:71]
	v_add_f32_dpp v72, v72, v72 row_ror:2 row_mask:0xf bank_mask:0xf bound_ctrl:1
	v_pk_mul_f32 v[184:185], v[44:45], v[4:5]
	v_pk_fma_f32 v[184:185], v[42:43], v[2:3], v[184:185]
	v_add_f32_dpp v72, v72, v72 row_ror:1 row_mask:0xf bank_mask:0xf bound_ctrl:1
	v_pk_fma_f32 v[2:3], v[10:11], v[72:73], v[68:69] op_sel_hi:[1,0,1]
	v_pk_fma_f32 v[4:5], v[12:13], v[72:73], v[70:71] op_sel_hi:[1,0,1]
	v_add_f32_e32 v187, v184, v185
	v_add_f32_dpp v63, v65, v65 row_ror:8 row_mask:0xf bank_mask:0xc bound_ctrl:1
	v_pk_mul_f32 v[26:27], v[2:3], v[26:27]
	v_pk_fma_f32 v[26:27], v[4:5], v[28:29], v[26:27]
	v_add_f32_e32 v72, v26, v27
	ds_read_b128 v[26:29], v50 offset:23360
	ds_read_b128 v[42:45], v50 offset:22528
	ds_read_b128 v[18:21], v50 offset:22272
	ds_read_b128 v[14:17], v50 offset:21504
	ds_read_b128 v[10:13], v50 offset:21760
	s_waitcnt lgkmcnt(5)
	v_add_f32_dpp v62, v62, v62 row_half_mirror row_mask:0xf bank_mask:0x5 bound_ctrl:1
	v_add_f32_dpp v72, v72, v72 row_ror:8 row_mask:0xf bank_mask:0xf bound_ctrl:1
	v_pk_mul_f32 v[68:69], v[38:39], v[60:61] op_sel:[0,1]
	v_pk_mul_f32 v[70:71], v[40:41], v[60:61] op_sel:[0,1]
	v_add_f32_dpp v72, v72, v72 row_ror:4 row_mask:0xf bank_mask:0xf bound_ctrl:1
	v_pk_fma_f32 v[68:69], v[2:3], v[34:35], v[68:69]
	v_pk_fma_f32 v[70:71], v[4:5], v[36:37], v[70:71]
	v_add_f32_dpp v72, v72, v72 row_ror:2 row_mask:0xf bank_mask:0xf bound_ctrl:1
	v_pk_mul_f32 v[184:185], v[192:193], v[4:5]
	v_pk_fma_f32 v[184:185], v[190:191], v[2:3], v[184:185]
	v_add_f32_dpp v72, v72, v72 row_ror:1 row_mask:0xf bank_mask:0xf bound_ctrl:1
	v_pk_fma_f32 v[2:3], v[30:31], v[72:73], v[68:69] op_sel_hi:[1,0,1]
	v_pk_fma_f32 v[4:5], v[32:33], v[72:73], v[70:71] op_sel_hi:[1,0,1]
	v_add_f32_e32 v188, v184, v185
	v_add_f32_dpp v62, v63, v63 row_half_mirror row_mask:0xf bank_mask:0xa bound_ctrl:1
	v_pk_mul_f32 v[6:7], v[2:3], v[6:7]
	v_pk_fma_f32 v[6:7], v[4:5], v[8:9], v[6:7]
	v_add_f32_e32 v72, v6, v7
	ds_read_b128 v[6:9], v50 offset:24704
	ds_read_b128 v[190:193], v50 offset:23872
	ds_read_b128 v[38:41], v50 offset:23616
	ds_read_b128 v[34:37], v50 offset:22848
	ds_read_b128 v[30:33], v50 offset:23104
	ds_read_b128 v[58:61], v51 offset:28160
	s_waitcnt lgkmcnt(6)
	v_add_f32_dpp v62, v62, v62 quad_perm:[1,0,3,2] row_mask:0xf bank_mask:0xf bound_ctrl:1
	v_add_f32_dpp v72, v72, v72 row_ror:8 row_mask:0xf bank_mask:0xf bound_ctrl:1
	v_pk_mul_f32 v[68:69], v[18:19], v[54:55] op_sel_hi:[1,0]
	v_pk_mul_f32 v[70:71], v[20:21], v[54:55] op_sel_hi:[1,0]
	v_add_f32_dpp v72, v72, v72 row_ror:4 row_mask:0xf bank_mask:0xf bound_ctrl:1
	v_pk_fma_f32 v[68:69], v[2:3], v[14:15], v[68:69]
	v_pk_fma_f32 v[70:71], v[4:5], v[16:17], v[70:71]
	v_add_f32_dpp v72, v72, v72 row_ror:2 row_mask:0xf bank_mask:0xf bound_ctrl:1
	v_pk_mul_f32 v[184:185], v[24:25], v[4:5]
	v_pk_fma_f32 v[184:185], v[22:23], v[2:3], v[184:185]
	v_add_f32_dpp v72, v72, v72 row_ror:1 row_mask:0xf bank_mask:0xf bound_ctrl:1
	v_pk_fma_f32 v[2:3], v[10:11], v[72:73], v[68:69] op_sel_hi:[1,0,1]
	v_pk_fma_f32 v[4:5], v[12:13], v[72:73], v[70:71] op_sel_hi:[1,0,1]
	v_add_f32_e32 v189, v184, v185
	v_add_f32_dpp v62, v62, v62 quad_perm:[2,3,0,1] row_mask:0xf bank_mask:0xf bound_ctrl:1
	v_pk_mul_f32 v[26:27], v[2:3], v[26:27]
	v_pk_fma_f32 v[26:27], v[4:5], v[28:29], v[26:27]
	v_add_f32_e32 v72, v26, v27
	ds_read_b128 v[26:29], v50 offset:26048
	ds_read_b128 v[22:25], v50 offset:25216
	ds_read_b128 v[18:21], v50 offset:24960
	ds_read_b128 v[14:17], v50 offset:24192
	ds_read_b128 v[10:13], v50 offset:24448
	s_waitcnt lgkmcnt(5)
	v_cndmask_b32_e64 v66, v66, v62, s[10:11]
	v_add_f32_dpp v186, v186, v186 row_ror:8 row_mask:0xf bank_mask:0x3 bound_ctrl:1
	v_add_f32_dpp v72, v72, v72 row_ror:8 row_mask:0xf bank_mask:0xf bound_ctrl:1
	v_pk_mul_f32 v[68:69], v[38:39], v[54:55] op_sel:[0,1]
	v_pk_mul_f32 v[70:71], v[40:41], v[54:55] op_sel:[0,1]
	v_add_f32_dpp v72, v72, v72 row_ror:4 row_mask:0xf bank_mask:0xf bound_ctrl:1
	v_pk_fma_f32 v[68:69], v[2:3], v[34:35], v[68:69]
	v_pk_fma_f32 v[70:71], v[4:5], v[36:37], v[70:71]
	v_add_f32_dpp v72, v72, v72 row_ror:2 row_mask:0xf bank_mask:0xf bound_ctrl:1
	v_pk_mul_f32 v[184:185], v[44:45], v[4:5]
	v_pk_fma_f32 v[184:185], v[42:43], v[2:3], v[184:185]
	v_add_f32_dpp v72, v72, v72 row_ror:1 row_mask:0xf bank_mask:0xf bound_ctrl:1
	v_pk_fma_f32 v[2:3], v[30:31], v[72:73], v[68:69] op_sel_hi:[1,0,1]
	v_pk_fma_f32 v[4:5], v[32:33], v[72:73], v[70:71] op_sel_hi:[1,0,1]
	v_add_f32_e32 v62, v184, v185
	v_add_f32_dpp v187, v187, v187 row_ror:8 row_mask:0xf bank_mask:0x3 bound_ctrl:1
	v_pk_mul_f32 v[6:7], v[2:3], v[6:7]
	v_pk_fma_f32 v[6:7], v[4:5], v[8:9], v[6:7]
	v_add_f32_e32 v72, v6, v7
	ds_read_b128 v[6:9], v50 offset:27392
	ds_read_b128 v[42:45], v50 offset:26560
	ds_read_b128 v[38:41], v50 offset:26304
	ds_read_b128 v[34:37], v50 offset:25536
	ds_read_b128 v[30:33], v50 offset:25792
	s_waitcnt lgkmcnt(5)
	v_add_f32_dpp v186, v188, v188 row_ror:8 row_mask:0xf bank_mask:0xc bound_ctrl:1
	v_add_f32_dpp v72, v72, v72 row_ror:8 row_mask:0xf bank_mask:0xf bound_ctrl:1
	v_pk_mul_f32 v[68:69], v[18:19], v[56:57] op_sel_hi:[1,0]
	v_pk_mul_f32 v[70:71], v[20:21], v[56:57] op_sel_hi:[1,0]
	v_add_f32_dpp v72, v72, v72 row_ror:4 row_mask:0xf bank_mask:0xf bound_ctrl:1
	v_pk_fma_f32 v[68:69], v[2:3], v[14:15], v[68:69]
	v_pk_fma_f32 v[70:71], v[4:5], v[16:17], v[70:71]
	v_add_f32_dpp v72, v72, v72 row_ror:2 row_mask:0xf bank_mask:0xf bound_ctrl:1
	v_pk_mul_f32 v[184:185], v[192:193], v[4:5]
	v_pk_fma_f32 v[184:185], v[190:191], v[2:3], v[184:185]
	v_add_f32_dpp v72, v72, v72 row_ror:1 row_mask:0xf bank_mask:0xf bound_ctrl:1
	v_pk_fma_f32 v[2:3], v[10:11], v[72:73], v[68:69] op_sel_hi:[1,0,1]
	v_pk_fma_f32 v[4:5], v[12:13], v[72:73], v[70:71] op_sel_hi:[1,0,1]
	v_add_f32_e32 v63, v184, v185
	v_add_f32_dpp v187, v189, v189 row_ror:8 row_mask:0xf bank_mask:0xc bound_ctrl:1
	v_pk_mul_f32 v[26:27], v[2:3], v[26:27]
	v_pk_fma_f32 v[26:27], v[4:5], v[28:29], v[26:27]
	v_add_f32_e32 v72, v26, v27
	ds_read_b128 v[26:29], v50 offset:28736
	ds_read_b128 v[190:193], v50 offset:27904
	ds_read_b128 v[18:21], v50 offset:27648
	ds_read_b128 v[14:17], v50 offset:26880
	ds_read_b128 v[10:13], v50 offset:27136
	s_waitcnt lgkmcnt(5)
	v_add_f32_dpp v186, v186, v186 row_half_mirror row_mask:0xf bank_mask:0x5 bound_ctrl:1
	v_add_f32_dpp v72, v72, v72 row_ror:8 row_mask:0xf bank_mask:0xf bound_ctrl:1
	v_pk_mul_f32 v[68:69], v[38:39], v[56:57] op_sel:[0,1]
	v_pk_mul_f32 v[70:71], v[40:41], v[56:57] op_sel:[0,1]
	v_add_f32_dpp v72, v72, v72 row_ror:4 row_mask:0xf bank_mask:0xf bound_ctrl:1
	v_pk_fma_f32 v[68:69], v[2:3], v[34:35], v[68:69]
	v_pk_fma_f32 v[70:71], v[4:5], v[36:37], v[70:71]
	v_add_f32_dpp v72, v72, v72 row_ror:2 row_mask:0xf bank_mask:0xf bound_ctrl:1
	v_pk_mul_f32 v[184:185], v[24:25], v[4:5]
	v_pk_fma_f32 v[184:185], v[22:23], v[2:3], v[184:185]
	v_add_f32_dpp v72, v72, v72 row_ror:1 row_mask:0xf bank_mask:0xf bound_ctrl:1
	v_pk_fma_f32 v[2:3], v[30:31], v[72:73], v[68:69] op_sel_hi:[1,0,1]
	v_pk_fma_f32 v[4:5], v[32:33], v[72:73], v[70:71] op_sel_hi:[1,0,1]
	v_add_f32_e32 v64, v184, v185
	v_add_f32_dpp v186, v187, v187 row_half_mirror row_mask:0xf bank_mask:0xa bound_ctrl:1
	v_pk_mul_f32 v[6:7], v[2:3], v[6:7]
	v_pk_fma_f32 v[6:7], v[4:5], v[8:9], v[6:7]
	v_add_f32_e32 v72, v6, v7
	ds_read_b128 v[6:9], v50 offset:30080
	ds_read_b128 v[22:25], v50 offset:29248
	ds_read_b128 v[38:41], v50 offset:28992
	ds_read_b128 v[34:37], v50 offset:28224
	ds_read_b128 v[30:33], v50 offset:28480
	ds_read_b128 v[54:57], v51 offset:33536
	s_waitcnt lgkmcnt(6)
	v_add_f32_dpp v186, v186, v186 quad_perm:[1,0,3,2] row_mask:0xf bank_mask:0xf bound_ctrl:1
	v_add_f32_dpp v72, v72, v72 row_ror:8 row_mask:0xf bank_mask:0xf bound_ctrl:1
	v_pk_mul_f32 v[68:69], v[18:19], v[58:59] op_sel_hi:[1,0]
	v_pk_mul_f32 v[70:71], v[20:21], v[58:59] op_sel_hi:[1,0]
	v_add_f32_dpp v72, v72, v72 row_ror:4 row_mask:0xf bank_mask:0xf bound_ctrl:1
	v_pk_fma_f32 v[68:69], v[2:3], v[14:15], v[68:69]
	v_pk_fma_f32 v[70:71], v[4:5], v[16:17], v[70:71]
	v_add_f32_dpp v72, v72, v72 row_ror:2 row_mask:0xf bank_mask:0xf bound_ctrl:1
	v_pk_mul_f32 v[184:185], v[44:45], v[4:5]
	v_pk_fma_f32 v[184:185], v[42:43], v[2:3], v[184:185]
	v_add_f32_dpp v72, v72, v72 row_ror:1 row_mask:0xf bank_mask:0xf bound_ctrl:1
	v_pk_fma_f32 v[2:3], v[10:11], v[72:73], v[68:69] op_sel_hi:[1,0,1]
	v_pk_fma_f32 v[4:5], v[12:13], v[72:73], v[70:71] op_sel_hi:[1,0,1]
	v_add_f32_e32 v65, v184, v185
	v_add_f32_dpp v186, v186, v186 quad_perm:[2,3,0,1] row_mask:0xf bank_mask:0xf bound_ctrl:1
	v_pk_mul_f32 v[26:27], v[2:3], v[26:27]
	v_pk_fma_f32 v[26:27], v[4:5], v[28:29], v[26:27]
	v_add_f32_e32 v72, v26, v27
	ds_read_b128 v[26:29], v50 offset:31424
	ds_read_b128 v[42:45], v50 offset:30592
	ds_read_b128 v[18:21], v50 offset:30336
	ds_read_b128 v[14:17], v50 offset:29568
	ds_read_b128 v[10:13], v50 offset:29824
	s_waitcnt lgkmcnt(5)
	v_cndmask_b32_e64 v66, v66, v186, s[12:13]
	ds_write_b32 v52, v66
	v_add_f32_dpp v62, v62, v62 row_ror:8 row_mask:0xf bank_mask:0x3 bound_ctrl:1
	v_add_f32_dpp v72, v72, v72 row_ror:8 row_mask:0xf bank_mask:0xf bound_ctrl:1
	v_pk_mul_f32 v[68:69], v[38:39], v[58:59] op_sel:[0,1]
	v_pk_mul_f32 v[70:71], v[40:41], v[58:59] op_sel:[0,1]
	v_add_f32_dpp v72, v72, v72 row_ror:4 row_mask:0xf bank_mask:0xf bound_ctrl:1
	v_pk_fma_f32 v[68:69], v[2:3], v[34:35], v[68:69]
	v_pk_fma_f32 v[70:71], v[4:5], v[36:37], v[70:71]
	v_add_f32_dpp v72, v72, v72 row_ror:2 row_mask:0xf bank_mask:0xf bound_ctrl:1
	v_pk_mul_f32 v[184:185], v[192:193], v[4:5]
	v_pk_fma_f32 v[184:185], v[190:191], v[2:3], v[184:185]
	v_add_f32_dpp v72, v72, v72 row_ror:1 row_mask:0xf bank_mask:0xf bound_ctrl:1
	v_pk_fma_f32 v[2:3], v[30:31], v[72:73], v[68:69] op_sel_hi:[1,0,1]
	v_pk_fma_f32 v[4:5], v[32:33], v[72:73], v[70:71] op_sel_hi:[1,0,1]
	v_add_f32_e32 v186, v184, v185
	v_add_f32_dpp v63, v63, v63 row_ror:8 row_mask:0xf bank_mask:0x3 bound_ctrl:1
	v_pk_mul_f32 v[6:7], v[2:3], v[6:7]
	v_pk_fma_f32 v[6:7], v[4:5], v[8:9], v[6:7]
	v_add_f32_e32 v72, v6, v7
	ds_read_b128 v[6:9], v50 offset:32768
	ds_read_b128 v[190:193], v50 offset:31936
	ds_read_b128 v[38:41], v50 offset:31680
	ds_read_b128 v[34:37], v50 offset:30912
	ds_read_b128 v[30:33], v50 offset:31168
	s_waitcnt lgkmcnt(5)
	v_add_f32_dpp v62, v64, v64 row_ror:8 row_mask:0xf bank_mask:0xc bound_ctrl:1
	v_add_f32_dpp v72, v72, v72 row_ror:8 row_mask:0xf bank_mask:0xf bound_ctrl:1
	v_pk_mul_f32 v[68:69], v[18:19], v[60:61] op_sel_hi:[1,0]
	v_pk_mul_f32 v[70:71], v[20:21], v[60:61] op_sel_hi:[1,0]
	v_add_f32_dpp v72, v72, v72 row_ror:4 row_mask:0xf bank_mask:0xf bound_ctrl:1
	v_pk_fma_f32 v[68:69], v[2:3], v[14:15], v[68:69]
	v_pk_fma_f32 v[70:71], v[4:5], v[16:17], v[70:71]
	v_add_f32_dpp v72, v72, v72 row_ror:2 row_mask:0xf bank_mask:0xf bound_ctrl:1
	v_pk_mul_f32 v[184:185], v[24:25], v[4:5]
	v_pk_fma_f32 v[184:185], v[22:23], v[2:3], v[184:185]
	v_add_f32_dpp v72, v72, v72 row_ror:1 row_mask:0xf bank_mask:0xf bound_ctrl:1
	v_pk_fma_f32 v[2:3], v[10:11], v[72:73], v[68:69] op_sel_hi:[1,0,1]
	v_pk_fma_f32 v[4:5], v[12:13], v[72:73], v[70:71] op_sel_hi:[1,0,1]
	v_add_f32_e32 v187, v184, v185
	v_add_f32_dpp v63, v65, v65 row_ror:8 row_mask:0xf bank_mask:0xc bound_ctrl:1
	v_pk_mul_f32 v[26:27], v[2:3], v[26:27]
	v_pk_fma_f32 v[26:27], v[4:5], v[28:29], v[26:27]
	v_add_f32_e32 v72, v26, v27
	ds_read_b128 v[26:29], v50 offset:34112
	ds_read_b128 v[22:25], v50 offset:33280
	ds_read_b128 v[18:21], v50 offset:33024
	ds_read_b128 v[14:17], v50 offset:32256
	ds_read_b128 v[10:13], v50 offset:32512
	s_waitcnt lgkmcnt(5)
	v_add_f32_dpp v62, v62, v62 row_half_mirror row_mask:0xf bank_mask:0x5 bound_ctrl:1
	v_add_f32_dpp v72, v72, v72 row_ror:8 row_mask:0xf bank_mask:0xf bound_ctrl:1
	v_pk_mul_f32 v[68:69], v[38:39], v[60:61] op_sel:[0,1]
	v_pk_mul_f32 v[70:71], v[40:41], v[60:61] op_sel:[0,1]
	v_add_f32_dpp v72, v72, v72 row_ror:4 row_mask:0xf bank_mask:0xf bound_ctrl:1
	v_pk_fma_f32 v[68:69], v[2:3], v[34:35], v[68:69]
	v_pk_fma_f32 v[70:71], v[4:5], v[36:37], v[70:71]
	v_add_f32_dpp v72, v72, v72 row_ror:2 row_mask:0xf bank_mask:0xf bound_ctrl:1
	v_pk_mul_f32 v[184:185], v[44:45], v[4:5]
	v_pk_fma_f32 v[184:185], v[42:43], v[2:3], v[184:185]
	v_add_f32_dpp v72, v72, v72 row_ror:1 row_mask:0xf bank_mask:0xf bound_ctrl:1
	v_pk_fma_f32 v[2:3], v[30:31], v[72:73], v[68:69] op_sel_hi:[1,0,1]
	v_pk_fma_f32 v[4:5], v[32:33], v[72:73], v[70:71] op_sel_hi:[1,0,1]
	v_add_f32_e32 v188, v184, v185
	v_add_f32_dpp v62, v63, v63 row_half_mirror row_mask:0xf bank_mask:0xa bound_ctrl:1
	v_pk_mul_f32 v[6:7], v[2:3], v[6:7]
	v_pk_fma_f32 v[6:7], v[4:5], v[8:9], v[6:7]
	v_add_f32_e32 v72, v6, v7
	ds_read_b128 v[6:9], v50 offset:35456
	ds_read_b128 v[42:45], v50 offset:34624
	ds_read_b128 v[38:41], v50 offset:34368
	ds_read_b128 v[34:37], v50 offset:33600
	ds_read_b128 v[30:33], v50 offset:33856
	ds_read_b128 v[58:61], v51 offset:38912
	s_waitcnt lgkmcnt(6)
	v_add_f32_dpp v62, v62, v62 quad_perm:[1,0,3,2] row_mask:0xf bank_mask:0xf bound_ctrl:1
	v_add_f32_dpp v72, v72, v72 row_ror:8 row_mask:0xf bank_mask:0xf bound_ctrl:1
	v_pk_mul_f32 v[68:69], v[18:19], v[54:55] op_sel_hi:[1,0]
	v_pk_mul_f32 v[70:71], v[20:21], v[54:55] op_sel_hi:[1,0]
	v_add_f32_dpp v72, v72, v72 row_ror:4 row_mask:0xf bank_mask:0xf bound_ctrl:1
	v_pk_fma_f32 v[68:69], v[2:3], v[14:15], v[68:69]
	v_pk_fma_f32 v[70:71], v[4:5], v[16:17], v[70:71]
	v_add_f32_dpp v72, v72, v72 row_ror:2 row_mask:0xf bank_mask:0xf bound_ctrl:1
	v_pk_mul_f32 v[184:185], v[192:193], v[4:5]
	v_pk_fma_f32 v[184:185], v[190:191], v[2:3], v[184:185]
	v_add_f32_dpp v72, v72, v72 row_ror:1 row_mask:0xf bank_mask:0xf bound_ctrl:1
	v_pk_fma_f32 v[2:3], v[10:11], v[72:73], v[68:69] op_sel_hi:[1,0,1]
	v_pk_fma_f32 v[4:5], v[12:13], v[72:73], v[70:71] op_sel_hi:[1,0,1]
	v_add_f32_e32 v189, v184, v185
	v_add_f32_dpp v62, v62, v62 quad_perm:[2,3,0,1] row_mask:0xf bank_mask:0xf bound_ctrl:1
	v_pk_mul_f32 v[26:27], v[2:3], v[26:27]
	v_pk_fma_f32 v[26:27], v[4:5], v[28:29], v[26:27]
	v_add_f32_e32 v72, v26, v27
	ds_read_b128 v[26:29], v50 offset:36800
	ds_read_b128 v[190:193], v50 offset:35968
	ds_read_b128 v[18:21], v50 offset:35712
	ds_read_b128 v[14:17], v50 offset:34944
	ds_read_b128 v[10:13], v50 offset:35200
	s_waitcnt lgkmcnt(5)
	v_cndmask_b32_e64 v66, 0, v62, s[6:7]
	v_add_f32_dpp v186, v186, v186 row_ror:8 row_mask:0xf bank_mask:0x3 bound_ctrl:1
	v_add_f32_dpp v72, v72, v72 row_ror:8 row_mask:0xf bank_mask:0xf bound_ctrl:1
	v_pk_mul_f32 v[68:69], v[38:39], v[54:55] op_sel:[0,1]
	v_pk_mul_f32 v[70:71], v[40:41], v[54:55] op_sel:[0,1]
	v_add_f32_dpp v72, v72, v72 row_ror:4 row_mask:0xf bank_mask:0xf bound_ctrl:1
	v_pk_fma_f32 v[68:69], v[2:3], v[34:35], v[68:69]
	v_pk_fma_f32 v[70:71], v[4:5], v[36:37], v[70:71]
	v_add_f32_dpp v72, v72, v72 row_ror:2 row_mask:0xf bank_mask:0xf bound_ctrl:1
	v_pk_mul_f32 v[184:185], v[24:25], v[4:5]
	v_pk_fma_f32 v[184:185], v[22:23], v[2:3], v[184:185]
	v_add_f32_dpp v72, v72, v72 row_ror:1 row_mask:0xf bank_mask:0xf bound_ctrl:1
	v_pk_fma_f32 v[2:3], v[30:31], v[72:73], v[68:69] op_sel_hi:[1,0,1]
	v_pk_fma_f32 v[4:5], v[32:33], v[72:73], v[70:71] op_sel_hi:[1,0,1]
	v_add_f32_e32 v62, v184, v185
	v_add_f32_dpp v187, v187, v187 row_ror:8 row_mask:0xf bank_mask:0x3 bound_ctrl:1
	v_pk_mul_f32 v[6:7], v[2:3], v[6:7]
	v_pk_fma_f32 v[6:7], v[4:5], v[8:9], v[6:7]
	v_add_f32_e32 v72, v6, v7
	ds_read_b128 v[6:9], v50 offset:38144
	ds_read_b128 v[22:25], v50 offset:37312
	ds_read_b128 v[38:41], v50 offset:37056
	ds_read_b128 v[34:37], v50 offset:36288
	ds_read_b128 v[30:33], v50 offset:36544
	s_waitcnt lgkmcnt(5)
	v_add_f32_dpp v186, v188, v188 row_ror:8 row_mask:0xf bank_mask:0xc bound_ctrl:1
	v_add_f32_dpp v72, v72, v72 row_ror:8 row_mask:0xf bank_mask:0xf bound_ctrl:1
	v_pk_mul_f32 v[68:69], v[18:19], v[56:57] op_sel_hi:[1,0]
	v_pk_mul_f32 v[70:71], v[20:21], v[56:57] op_sel_hi:[1,0]
	v_add_f32_dpp v72, v72, v72 row_ror:4 row_mask:0xf bank_mask:0xf bound_ctrl:1
	v_pk_fma_f32 v[68:69], v[2:3], v[14:15], v[68:69]
	v_pk_fma_f32 v[70:71], v[4:5], v[16:17], v[70:71]
	v_add_f32_dpp v72, v72, v72 row_ror:2 row_mask:0xf bank_mask:0xf bound_ctrl:1
	v_pk_mul_f32 v[184:185], v[44:45], v[4:5]
	v_pk_fma_f32 v[184:185], v[42:43], v[2:3], v[184:185]
	v_add_f32_dpp v72, v72, v72 row_ror:1 row_mask:0xf bank_mask:0xf bound_ctrl:1
	v_pk_fma_f32 v[2:3], v[10:11], v[72:73], v[68:69] op_sel_hi:[1,0,1]
	v_pk_fma_f32 v[4:5], v[12:13], v[72:73], v[70:71] op_sel_hi:[1,0,1]
	v_add_f32_e32 v63, v184, v185
	v_add_f32_dpp v187, v189, v189 row_ror:8 row_mask:0xf bank_mask:0xc bound_ctrl:1
	v_pk_mul_f32 v[26:27], v[2:3], v[26:27]
	v_pk_fma_f32 v[26:27], v[4:5], v[28:29], v[26:27]
	v_add_f32_e32 v72, v26, v27
	ds_read_b128 v[26:29], v50 offset:39488
	ds_read_b128 v[42:45], v50 offset:38656
	ds_read_b128 v[18:21], v50 offset:38400
	ds_read_b128 v[14:17], v50 offset:37632
	ds_read_b128 v[10:13], v50 offset:37888
	s_waitcnt lgkmcnt(5)
	v_add_f32_dpp v186, v186, v186 row_half_mirror row_mask:0xf bank_mask:0x5 bound_ctrl:1
	v_add_f32_dpp v72, v72, v72 row_ror:8 row_mask:0xf bank_mask:0xf bound_ctrl:1
	v_pk_mul_f32 v[68:69], v[38:39], v[56:57] op_sel:[0,1]
	v_pk_mul_f32 v[70:71], v[40:41], v[56:57] op_sel:[0,1]
	v_add_f32_dpp v72, v72, v72 row_ror:4 row_mask:0xf bank_mask:0xf bound_ctrl:1
	v_pk_fma_f32 v[68:69], v[2:3], v[34:35], v[68:69]
	v_pk_fma_f32 v[70:71], v[4:5], v[36:37], v[70:71]
	v_add_f32_dpp v72, v72, v72 row_ror:2 row_mask:0xf bank_mask:0xf bound_ctrl:1
	v_pk_mul_f32 v[184:185], v[192:193], v[4:5]
	v_pk_fma_f32 v[184:185], v[190:191], v[2:3], v[184:185]
	v_add_f32_dpp v72, v72, v72 row_ror:1 row_mask:0xf bank_mask:0xf bound_ctrl:1
	v_pk_fma_f32 v[2:3], v[30:31], v[72:73], v[68:69] op_sel_hi:[1,0,1]
	v_pk_fma_f32 v[4:5], v[32:33], v[72:73], v[70:71] op_sel_hi:[1,0,1]
	v_add_f32_e32 v64, v184, v185
	v_add_f32_dpp v186, v187, v187 row_half_mirror row_mask:0xf bank_mask:0xa bound_ctrl:1
	v_pk_mul_f32 v[6:7], v[2:3], v[6:7]
	v_pk_fma_f32 v[6:7], v[4:5], v[8:9], v[6:7]
	v_add_f32_e32 v72, v6, v7
	ds_read_b128 v[6:9], v50 offset:40832
	ds_read_b128 v[190:193], v50 offset:40000
	ds_read_b128 v[38:41], v50 offset:39744
	ds_read_b128 v[34:37], v50 offset:38976
	ds_read_b128 v[30:33], v50 offset:39232
	s_waitcnt lgkmcnt(5)
	v_add_f32_dpp v186, v186, v186 quad_perm:[1,0,3,2] row_mask:0xf bank_mask:0xf bound_ctrl:1
	v_add_f32_dpp v72, v72, v72 row_ror:8 row_mask:0xf bank_mask:0xf bound_ctrl:1
	v_pk_mul_f32 v[68:69], v[18:19], v[58:59] op_sel_hi:[1,0]
	v_pk_mul_f32 v[70:71], v[20:21], v[58:59] op_sel_hi:[1,0]
	v_add_f32_dpp v72, v72, v72 row_ror:4 row_mask:0xf bank_mask:0xf bound_ctrl:1
	v_pk_fma_f32 v[68:69], v[2:3], v[14:15], v[68:69]
	v_pk_fma_f32 v[70:71], v[4:5], v[16:17], v[70:71]
	v_add_f32_dpp v72, v72, v72 row_ror:2 row_mask:0xf bank_mask:0xf bound_ctrl:1
	v_pk_mul_f32 v[184:185], v[24:25], v[4:5]
	v_pk_fma_f32 v[184:185], v[22:23], v[2:3], v[184:185]
	v_add_f32_dpp v72, v72, v72 row_ror:1 row_mask:0xf bank_mask:0xf bound_ctrl:1
	v_pk_fma_f32 v[2:3], v[10:11], v[72:73], v[68:69] op_sel_hi:[1,0,1]
	v_pk_fma_f32 v[4:5], v[12:13], v[72:73], v[70:71] op_sel_hi:[1,0,1]
	v_add_f32_e32 v65, v184, v185
	v_add_f32_dpp v186, v186, v186 quad_perm:[2,3,0,1] row_mask:0xf bank_mask:0xf bound_ctrl:1
	v_pk_mul_f32 v[26:27], v[2:3], v[26:27]
	v_pk_fma_f32 v[26:27], v[4:5], v[28:29], v[26:27]
	v_add_f32_e32 v72, v26, v27
	ds_read_b128 v[26:29], v50 offset:42176
	ds_read_b128 v[22:25], v50 offset:41344
	ds_read_b128 v[18:21], v50 offset:41088
	ds_read_b128 v[14:17], v50 offset:40320
	ds_read_b128 v[10:13], v50 offset:40576
	s_waitcnt lgkmcnt(5)
	v_cndmask_b32_e64 v66, v66, v186, s[8:9]
	v_add_f32_dpp v62, v62, v62 row_ror:8 row_mask:0xf bank_mask:0x3 bound_ctrl:1
	v_add_f32_dpp v72, v72, v72 row_ror:8 row_mask:0xf bank_mask:0xf bound_ctrl:1
	v_pk_mul_f32 v[68:69], v[38:39], v[58:59] op_sel:[0,1]
	v_pk_mul_f32 v[70:71], v[40:41], v[58:59] op_sel:[0,1]
	v_add_f32_dpp v72, v72, v72 row_ror:4 row_mask:0xf bank_mask:0xf bound_ctrl:1
	v_pk_fma_f32 v[68:69], v[2:3], v[34:35], v[68:69]
	v_pk_fma_f32 v[70:71], v[4:5], v[36:37], v[70:71]
	v_add_f32_dpp v72, v72, v72 row_ror:2 row_mask:0xf bank_mask:0xf bound_ctrl:1
	v_pk_mul_f32 v[184:185], v[44:45], v[4:5]
	v_pk_fma_f32 v[184:185], v[42:43], v[2:3], v[184:185]
	v_add_f32_dpp v72, v72, v72 row_ror:1 row_mask:0xf bank_mask:0xf bound_ctrl:1
	v_pk_fma_f32 v[2:3], v[30:31], v[72:73], v[68:69] op_sel_hi:[1,0,1]
	v_pk_fma_f32 v[4:5], v[32:33], v[72:73], v[70:71] op_sel_hi:[1,0,1]
	v_add_f32_e32 v186, v184, v185
	v_add_f32_dpp v63, v63, v63 row_ror:8 row_mask:0xf bank_mask:0x3 bound_ctrl:1
	v_pk_mul_f32 v[6:7], v[2:3], v[6:7]
	v_pk_fma_f32 v[6:7], v[4:5], v[8:9], v[6:7]
	v_add_f32_e32 v72, v6, v7
	ds_read_b128 v[42:45], v50 offset:42688
	ds_read_b128 v[38:41], v50 offset:42432
	ds_read_b128 v[34:37], v50 offset:41664
	ds_read_b128 v[30:33], v50 offset:41920
	s_waitcnt lgkmcnt(4)
	v_add_f32_dpp v62, v64, v64 row_ror:8 row_mask:0xf bank_mask:0xc bound_ctrl:1
	v_add_f32_dpp v72, v72, v72 row_ror:8 row_mask:0xf bank_mask:0xf bound_ctrl:1
	v_pk_mul_f32 v[68:69], v[18:19], v[60:61] op_sel_hi:[1,0]
	v_pk_mul_f32 v[70:71], v[20:21], v[60:61] op_sel_hi:[1,0]
	v_add_f32_dpp v72, v72, v72 row_ror:4 row_mask:0xf bank_mask:0xf bound_ctrl:1
	v_pk_fma_f32 v[68:69], v[2:3], v[14:15], v[68:69]
	v_pk_fma_f32 v[70:71], v[4:5], v[16:17], v[70:71]
	v_add_f32_dpp v72, v72, v72 row_ror:2 row_mask:0xf bank_mask:0xf bound_ctrl:1
	v_pk_mul_f32 v[184:185], v[192:193], v[4:5]
	v_pk_fma_f32 v[184:185], v[190:191], v[2:3], v[184:185]
	v_add_f32_dpp v72, v72, v72 row_ror:1 row_mask:0xf bank_mask:0xf bound_ctrl:1
	v_pk_fma_f32 v[2:3], v[10:11], v[72:73], v[68:69] op_sel_hi:[1,0,1]
	v_pk_fma_f32 v[4:5], v[12:13], v[72:73], v[70:71] op_sel_hi:[1,0,1]
	v_add_f32_e32 v187, v184, v185
	v_add_f32_dpp v63, v65, v65 row_ror:8 row_mask:0xf bank_mask:0xc bound_ctrl:1
	v_pk_mul_f32 v[26:27], v[2:3], v[26:27]
	v_pk_fma_f32 v[26:27], v[4:5], v[28:29], v[26:27]
	v_add_f32_e32 v72, v26, v27
	s_waitcnt lgkmcnt(0)
	v_add_f32_dpp v62, v62, v62 row_half_mirror row_mask:0xf bank_mask:0x5 bound_ctrl:1
	v_add_f32_dpp v72, v72, v72 row_ror:8 row_mask:0xf bank_mask:0xf bound_ctrl:1
	v_pk_mul_f32 v[68:69], v[38:39], v[60:61] op_sel:[0,1]
	v_pk_mul_f32 v[70:71], v[40:41], v[60:61] op_sel:[0,1]
	v_add_f32_dpp v72, v72, v72 row_ror:4 row_mask:0xf bank_mask:0xf bound_ctrl:1
	v_pk_fma_f32 v[68:69], v[2:3], v[34:35], v[68:69]
	v_pk_fma_f32 v[70:71], v[4:5], v[36:37], v[70:71]
	v_add_f32_dpp v72, v72, v72 row_ror:2 row_mask:0xf bank_mask:0xf bound_ctrl:1
	v_pk_mul_f32 v[184:185], v[24:25], v[4:5]
	v_pk_fma_f32 v[184:185], v[22:23], v[2:3], v[184:185]
	v_add_f32_dpp v72, v72, v72 row_ror:1 row_mask:0xf bank_mask:0xf bound_ctrl:1
	v_pk_fma_f32 v[2:3], v[30:31], v[72:73], v[68:69] op_sel_hi:[1,0,1]
	v_pk_fma_f32 v[4:5], v[32:33], v[72:73], v[70:71] op_sel_hi:[1,0,1]
	v_add_f32_e32 v188, v184, v185
	v_add_f32_dpp v62, v63, v63 row_half_mirror row_mask:0xf bank_mask:0xa bound_ctrl:1
	s_waitcnt lgkmcnt(0)
	v_pk_mul_f32 v[184:185], v[44:45], v[4:5]
	v_pk_fma_f32 v[184:185], v[42:43], v[2:3], v[184:185]
	v_add_f32_e32 v189, v184, v185
	v_add_f32_dpp v62, v62, v62 quad_perm:[1,0,3,2] row_mask:0xf bank_mask:0xf bound_ctrl:1
	s_nop 0
	s_nop 0
	v_add_f32_dpp v62, v62, v62 quad_perm:[2,3,0,1] row_mask:0xf bank_mask:0xf bound_ctrl:1
	v_cndmask_b32_e64 v66, v66, v62, s[10:11]
	v_add_f32_dpp v186, v186, v186 row_ror:8 row_mask:0xf bank_mask:0x3 bound_ctrl:1
	v_add_f32_dpp v187, v187, v187 row_ror:8 row_mask:0xf bank_mask:0x3 bound_ctrl:1
	s_nop 0
	v_add_f32_dpp v186, v188, v188 row_ror:8 row_mask:0xf bank_mask:0xc bound_ctrl:1
	v_add_f32_dpp v187, v189, v189 row_ror:8 row_mask:0xf bank_mask:0xc bound_ctrl:1
	s_nop 0
	v_add_f32_dpp v186, v186, v186 row_half_mirror row_mask:0xf bank_mask:0x5 bound_ctrl:1
	s_nop 0
	s_nop 0
	v_add_f32_dpp v186, v187, v187 row_half_mirror row_mask:0xf bank_mask:0xa bound_ctrl:1
	s_nop 0
	s_nop 0
	v_add_f32_dpp v186, v186, v186 quad_perm:[1,0,3,2] row_mask:0xf bank_mask:0xf bound_ctrl:1
	s_nop 0
	s_nop 0
	v_add_f32_dpp v186, v186, v186 quad_perm:[2,3,0,1] row_mask:0xf bank_mask:0xf bound_ctrl:1
	v_cndmask_b32_e64 v66, v66, v186, s[12:13]
	ds_write_b32 v52, v66 offset:1024
	s_cmp_ge_u32 s50, s51
	s_waitcnt lgkmcnt(0)
	s_barrier
	s_cbranch_scc0 .LBB0_2881
	s_setprio 0
	s_and_b64 vcc, exec, s[16:17]
	s_cbranch_vccz .LBB0_2884
	s_lshl_b32 s2, s42, 6
	s_lshl_b32 s4, s43, 4
	s_or_b32 s44, s2, s4
	v_ashrrev_i32_e32 v47, 31, v46
	v_lshl_add_u64 v[6:7], s[44:45], 0, v[46:47]
	v_lshlrev_b64 v[6:7], 8, v[6:7]
	v_lshl_add_u64 v[6:7], s[14:15], 0, v[6:7]
	v_lshl_add_u64 v[6:7], v[6:7], 0, v[0:1]
	v_add_co_u32_e32 v6, vcc, 0x5800000, v6
	s_nop 1
	v_addc_co_u32_e32 v7, vcc, 0, v7, vcc
	global_store_dwordx4 v[6:7], v[2:5], off
